# attention item header: per-head sink value requested one item ahead; the header wait leaves the previous item's two output stores outstanding
# baseline (speedup 1.0000x reference)
; DEVI void attn_item(const P& p, int item, char* smem) {
;     const int tid = threadIdx.x, lane = tid & 63, w = tid >> 6, fr = lane & 15, fq = lane >> 4;
;     const int qt = item & 63, kvh = (item >> 6) & 3, b = item >> 8;
;     const int head = kvh * 4 + w, q0 = qt * 64;
;     const bf16_t* Q = (const bf16_t*)(p.ws + OFF_B) + ((size_t)(b * SEQ + q0)) * 1024 + head * 64;
;     const bf16_t* KB = (const bf16_t*)(p.ws + OFF_D);
;     const bf16_t* VT = (const bf16_t*)(p.ws + OFF_D + 17 * MiB);
;     char* sK = smem;
;     char* sV = smem + 8192;
;     const float sinkv = p.sink[head] * LOG2E;
;     const bf16_t* SGT = (const bf16_t*)(p.ws + OFF_C) + ((size_t)(b * SEQ + q0)) * 1024 + head * 64;
;     bf16_t* OG = (bf16_t*)(p.ws + OFF_A) + ((size_t)(b * SEQ + q0)) * 1024 + head * 64;
.LBB0_1427:
	s_or_b64 exec, exec, s[2:3]
	s_cmpk_gt_i32 s86, 0x7ff
	s_barrier
	s_cbranch_scc1 .LBB0_1444
	v_xor_b32_e32 v4, v216, v172
	v_lshlrev_b32_e32 v4, 4, v4
	v_and_b32_e32 v4, 0x70, v4
	v_bfe_u32 v3, v172, 4, 2
	v_add_u32_e32 v123, 0, v4
	v_and_b32_e32 v4, 7, v172
	v_mov_b32_e32 v1, 0
	s_movk_i32 s2, 0x70
	v_and_b32_e32 v0, 0x70, v182
	v_and_b32_e32 v6, 14, v172
	v_bitop3_b32 v7, v175, v4, 3 bitop3:0x6c
	v_bitop3_b32 v4, v3, v4, 4 bitop3:0x36
	v_lshl_add_u64 v[98:99], s[54:55], 0, v[0:1]
	v_lshl_add_u64 v[100:101], s[0:1], 0, v[0:1]
	v_bitop3_b32 v0, v182, s2, v172 bitop3:0x48
	v_lshlrev_b32_e32 v125, 2, v3
	v_lshlrev_b32_e32 v8, 4, v4
	v_bitop3_b32 v4, v175, v6, 3 bitop3:0x6c
	v_add_u32_e32 v124, 0, v0
	v_sub_u32_e32 v0, v174, v125
	v_lshlrev_b32_e32 v9, 3, v4
	v_bitop3_b32 v4, v3, v6, 4 bitop3:0x36
	v_lshlrev_b32_e32 v2, 3, v3
	v_cmp_eq_u32_e32 vcc, 0, v3
	v_add_u32_e32 v126, 0x7f, v0
	v_lshrrev_b32_e32 v0, 2, v172
	v_lshlrev_b32_e32 v10, 3, v4
	v_bitop3_b32 v4, v3, v6, 8 bitop3:0x36
	v_bitop3_b32 v3, v3, v6, 12 bitop3:0x36
	v_lshl_add_u32 v5, v174, 7, 0
	v_and_b32_e32 v0, 8, v0
	v_add_u32_e32 v128, 32, v216
	v_lshlrev_b32_e32 v7, 4, v7
	v_lshlrev_b32_e32 v11, 3, v4
	v_lshlrev_b32_e32 v3, 3, v3
	v_and_b32_e32 v4, 16, v172
	s_mov_b32 s29, 0
	v_cndmask_b32_e64 v121, 0, 1.0, vcc
	v_lshlrev_b32_e32 v127, 7, v216
	v_lshlrev_b32_e32 v129, 7, v128
	s_lshl_b32 s34, s86, 6
	s_lshl_b32 s35, s27, 6
	v_lshlrev_b32_e32 v102, 1, v2
	v_mov_b32_e32 v103, v1
	v_lshlrev_b32_e32 v104, 1, v0
	v_mov_b32_e32 v105, v1
	s_movk_i32 s36, 0x2200
	v_lshlrev_b32_e32 v106, 1, v4
	v_mov_b32_e32 v107, v1
	v_add_u32_e32 v130, v5, v7
	v_add_u32_e32 v131, v5, v8
	s_movk_i32 s37, 0xfeff
	s_movk_i32 s38, 0x101
	s_movk_i32 s39, 0xfefe
	v_add_u32_e32 v132, v5, v9
	v_add_u32_e32 v133, v5, v10
	v_add_u32_e32 v134, v5, v11
	v_add_u32_e32 v135, v5, v3
	v_and_b32_e32 v2, 7, v172
	v_and_b32_e32 v3, 4, v2
	v_and_b32_e32 v4, 1, v2
	v_lshl_or_b32 v3, v4, 1, v3
	v_bfe_u32 v4, v216, 1, 3
	v_xor_b32_e32 v3, v3, v4
	v_bfe_u32 v4, v2, 1, 1
	v_lshlrev_b32_e32 v4, 3, v4
	v_lshl_or_b32 v124, v3, 4, v4
	v_xor_b32_e32 v228, 16, v124
	v_bfe_u32 v2, v172, 4, 2
	v_bfe_u32 v3, v174, 1, 3
	v_xor_b32_e32 v2, v2, v3
	v_lshl_add_u32 v132, v2, 4, v5
	v_xor_b32_e32 v134, 64, v132
	v_add_u32_e32 v133, v123, v127
	v_add_u32_e32 v135, v124, v127
	v_add_u32_e32 v217, v123, v129
	v_add_u32_e32 v229, v124, v129
	v_add_u32_e32 v214, v228, v127
	v_add_u32_e32 v215, v228, v129
	v_mov_b32_e32 v136, 0xf149f2ca
	s_mov_b32 s42, s86
	s_mov_b32 s99, 0
	s_bfe_u32 s0, s42, 0x20006
	v_lshl_add_u32 v253, s0, 2, v179
	v_lshlrev_b32_e32 v253, 2, v253
	global_load_dword v252, v253, s[84:85]
	s_waitcnt vmcnt(0)
	s_branch .LBB0_1430

; DEVI void attn_item(const P& p, int item, char* smem) {
;     const int tid = threadIdx.x, lane = tid & 63, w = tid >> 6, fr = lane & 15, fq = lane >> 4;
;     const int qt = item & 63, kvh = (item >> 6) & 3, b = item >> 8;
;     const int head = kvh * 4 + w, q0 = qt * 64;
;     const bf16_t* Q = (const bf16_t*)(p.ws + OFF_B) + ((size_t)(b * SEQ + q0)) * 1024 + head * 64;
;     const bf16_t* KB = (const bf16_t*)(p.ws + OFF_D);
;     const bf16_t* VT = (const bf16_t*)(p.ws + OFF_D + 17 * MiB);
;     char* sK = smem;
;     char* sV = smem + 8192;
;     const float sinkv = p.sink[head] * LOG2E;
;     const bf16_t* SGT = (const bf16_t*)(p.ws + OFF_C) + ((size_t)(b * SEQ + q0)) * 1024 + head * 64;
;     bf16_t* OG = (bf16_t*)(p.ws + OFF_A) + ((size_t)(b * SEQ + q0)) * 1024 + head * 64;
.LBB0_1430:
	s_bfe_u32 s6, s42, 0x20006
	v_lshl_add_u32 v0, s6, 2, v179
	s_ashr_i32 s46, s42, 8
	s_lshl_b32 s0, s42, 6
	s_and_b32 s1, s0, 0xfc0
	s_lshl_b32 s0, s46, 12
	s_or_b32 s0, s0, s1
	s_and_b32 s43, s34, 0xfc0
	v_add_u32_e32 v137, s1, v126
	s_ashr_i32 s1, s0, 31
	s_addk_i32 s43, 0x80
	s_lshl_b64 s[0:1], s[0:1], 11
	s_add_u32 s4, s80, s0
	v_lshlrev_b32_e32 v0, 7, v0
	s_addc_u32 s5, s81, s1
	v_lshl_add_u64 v[2:3], s[4:5], 0, v[0:1]
	s_add_u32 s4, s82, s0
	s_addc_u32 s5, s83, s1
	s_add_u32 s0, s90, s0
	v_lshl_add_u64 v[110:111], s[4:5], 0, v[0:1]
	s_addc_u32 s1, s91, s1
	s_lshl_b32 s4, s6, 6
	s_and_b32 s5, s42, 0xffffff00
	v_lshl_add_u64 v[108:109], v[2:3], 0, v[102:103]
	v_lshl_add_u64 v[2:3], s[0:1], 0, v[0:1]
	s_or_b32 s0, s4, s5
	s_lshl_b32 s28, s6, 7
	v_lshl_add_u64 v[2:3], v[2:3], 0, v[104:105]
	v_add_u32_e32 v0, s0, v216
	v_add_u32_e32 v5, s0, v128
	s_mov_b64 s[2:3], -1
	s_mulk_i32 s46, 0x1100
	v_lshl_add_u64 v[112:113], v[98:99], 0, s[28:29]
	v_lshlrev_b32_e32 v226, 9, v216
	v_mov_b32_e32 v227, 0
	v_lshl_add_u64 v[226:227], v[112:113], 0, v[226:227]
	v_mad_i64_i32 v[114:115], s[0:1], v0, s36, 0
	v_mad_i64_i32 v[116:117], s[0:1], v5, s36, 0
	v_lshl_add_u64 v[118:119], v[2:3], 0, v[106:107]
	s_mov_b32 s4, 0
	s_waitcnt vmcnt(2)
	v_mul_f32_e32 v138, 0x3fb8aa3b, v252
	s_add_i32 s0, s42, s27
	s_bfe_u32 s0, s0, 0x20006
	v_lshl_add_u32 v253, s0, 2, v179
	v_lshlrev_b32_e32 v253, 2, v253
	global_load_dword v252, v253, s[84:85]
	s_branch .LBB0_1432
